# attention loop: first four PV MFMAs issued right after the barrier on V fragments prefetched before it (hides K-fragment LDS latency); PV section MFMA/VALU order rebalanced
# baseline (speedup 1.0000x reference)
.LBB0_1320:
	v_readfirstlane_b32 s67, v107
	s_ashr_i32 s61, s67, 6
	s_lshl_b32 s66, s61, 4
	s_and_b32 s70, s66, 48
	v_or_b32_e32 v129, s70, v109
	v_mul_u32_u24_e32 v0, s49, v129
	s_ashr_i32 s23, s67, 8
	v_lshlrev_b32_e32 v0, 1, v0
	v_lshl_add_u64 v[2:3], s[30:31], 0, v[0:1]
	s_lshl_b32 s30, s23, 6
	s_ashr_i32 s31, s30, 31
	v_mul_lo_u32 v8, s49, v120
	v_lshl_add_u64 v[2:3], s[30:31], 1, v[2:3]
	s_lshl_b32 s31, s61, 10
	s_waitcnt vmcnt(0)
	v_mul_lo_u32 v10, s0, v122
	v_mov_b32_e32 v113, v1
	v_add_lshl_u32 v0, v8, v121, 1
	s_add_i32 s76, s2, s31
	v_lshl_add_u64 v[6:7], v[2:3], 0, v[112:113]
	v_add_lshl_u32 v8, v123, v10, 1
	v_lshl_add_u64 v[10:11], s[34:35], 0, v[0:1]
	s_mov_b32 m0, s76
	v_mul_lo_u32 v9, s0, v120
	global_load_dwordx4 v[2:5], v[6:7], off
	global_load_dwordx4 v[14:17], v[6:7], off offset:64
	s_barrier
	s_add_i32 s0, s76, 0xc000
	global_load_lds_dwordx4 v0, s[34:35]
	v_lshl_add_u64 v[10:11], v[10:11], 0, s[44:45]
	s_add_i32 m0, s76, 0x2000
	v_add_lshl_u32 v6, v9, v121, 1
	global_load_lds_dwordx4 v[10:11], off
	s_mov_b32 m0, s0
	s_add_i32 s0, s59, s31
	global_load_lds_dwordx4 v6, s[36:37]
	s_add_i32 m0, s76, 0xe000
	s_lshl_b32 s74, s49, 7
	global_load_lds_dwordx4 v8, s[36:37]
	s_add_i32 m0, s76, 0x4000
	s_add_u32 s50, s34, s74
	s_addc_u32 s51, s35, 0
	v_mov_b32_e32 v7, v1
	s_waitcnt vmcnt(0)
	v_lshl_add_u64 v[18:19], s[50:51], 0, v[0:1]
	v_lshl_add_u64 v[10:11], s[36:37], 0, v[6:7]
	v_mov_b32_e32 v9, v1
	global_load_lds_dwordx4 v0, s[50:51]
	v_lshl_add_u64 v[18:19], v[18:19], 0, s[44:45]
	s_add_i32 m0, s76, 0x6000
	v_lshl_add_u64 v[12:13], s[36:37], 0, v[8:9]
	global_load_lds_dwordx4 v[18:19], off
	v_lshl_add_u64 v[18:19], v[10:11], 0, s[44:45]
	s_mov_b32 m0, s0
	s_mov_b32 s77, 1
	global_load_lds_dwordx4 v[18:19], off
	v_lshl_add_u64 v[18:19], v[12:13], 0, s[44:45]
	s_add_i32 m0, s0, 0x2000
	s_add_i32 s0, s60, s31
	global_load_lds_dwordx4 v[18:19], off
	s_add_i32 m0, s76, 0x8000
	s_add_u32 s50, s50, s74
	s_addc_u32 s51, s51, 0
	v_lshl_add_u64 v[18:19], s[50:51], 0, v[0:1]
	global_load_lds_dwordx4 v0, s[50:51]
	v_lshl_add_u64 v[18:19], v[18:19], 0, s[44:45]
	s_add_i32 m0, s76, 0xa000
	s_mov_b64 s[50:51], 0x100
	global_load_lds_dwordx4 v[18:19], off
	v_lshl_add_u64 v[10:11], v[10:11], 0, s[50:51]
	s_mov_b32 m0, s0
	s_nop 0
	global_load_lds_dwordx4 v[10:11], off
	v_lshl_add_u64 v[10:11], v[12:13], 0, s[50:51]
	s_add_i32 m0, s0, 0x2000
	s_nop 0
	global_load_lds_dwordx4 v[10:11], off
	v_lshlrev_b32_e32 v10, 16, v2
	v_and_b32_e32 v11, 0xffff0000, v2
	s_mov_b32 s0, 0x3e38aa3b
	v_lshlrev_b32_e32 v2, 16, v3
	v_and_b32_e32 v3, 0xffff0000, v3
	v_pk_mul_f32 v[10:11], v[10:11], s[0:1] op_sel_hi:[1,0]
	v_pk_mul_f32 v[2:3], v[2:3], s[0:1] op_sel_hi:[1,0]
	v_cvt_pk_bf16_f32 v10, v10, v11
	v_cvt_pk_bf16_f32 v11, v2, v3
	v_lshlrev_b32_e32 v2, 16, v4
	v_and_b32_e32 v3, 0xffff0000, v4
	v_pk_mul_f32 v[2:3], v[2:3], s[0:1] op_sel_hi:[1,0]
	s_lshl_b32 s50, s23, 13
	v_cvt_pk_bf16_f32 v12, v2, v3
	v_lshlrev_b32_e32 v2, 16, v5
	v_and_b32_e32 v3, 0xffff0000, v5
	v_pk_mul_f32 v[2:3], v[2:3], s[0:1] op_sel_hi:[1,0]
	s_waitcnt vmcnt(8)
	s_barrier
	v_cvt_pk_bf16_f32 v13, v2, v3
	v_lshlrev_b32_e32 v2, 16, v14
	v_and_b32_e32 v3, 0xffff0000, v14
	v_pk_mul_f32 v[2:3], v[2:3], s[0:1] op_sel_hi:[1,0]
	v_add_u32_e32 v34, s50, v124
	v_cvt_pk_bf16_f32 v18, v2, v3
	v_lshlrev_b32_e32 v2, 16, v15
	v_and_b32_e32 v3, 0xffff0000, v15
	v_pk_mul_f32 v[14:15], v[2:3], s[0:1] op_sel_hi:[1,0]
	ds_read_b128 v[2:5], v34
	ds_read_b128 v[22:25], v34 offset:1024
	v_cvt_pk_bf16_f32 v19, v14, v15
	v_lshlrev_b32_e32 v14, 16, v16
	v_and_b32_e32 v15, 0xffff0000, v16
	v_pk_mul_f32 v[14:15], v[14:15], s[0:1] op_sel_hi:[1,0]
	v_lshlrev_b32_e32 v26, 16, v17
	v_cvt_pk_bf16_f32 v20, v14, v15
	v_and_b32_e32 v27, 0xffff0000, v17
	s_waitcnt lgkmcnt(0)
	v_mfma_f32_16x16x32_bf16 v[2:5], v[2:5], v[10:13], 0
	ds_read_b128 v[14:17], v34 offset:2048
	v_pk_mul_f32 v[26:27], v[26:27], s[0:1] op_sel_hi:[1,0]
	ds_read_b128 v[30:33], v34 offset:6144
	v_cvt_pk_bf16_f32 v21, v26, v27
	ds_read_b128 v[26:29], v34 offset:4096
	s_waitcnt lgkmcnt(0)
	v_mfma_f32_16x16x32_bf16 v[30:33], v[30:33], v[10:13], 0
	s_add_i32 s0, s71, -2
	s_mulk_i32 s49, 0x180
	s_add_u32 s34, s34, s49
	v_mfma_f32_16x16x32_bf16 v[22:25], v[22:25], v[18:21], v[2:5]
	s_addc_u32 s35, s35, 0
	v_lshl_add_u64 v[114:115], s[34:35], 0, v[0:1]
	s_add_u32 s34, s36, 0x180
	ds_read_b128 v[2:5], v34 offset:3072
	v_mfma_f32_16x16x32_bf16 v[14:17], v[14:17], v[10:13], 0
	s_mov_b32 s88, s75
	s_mov_b32 s89, s75
	s_addc_u32 s35, s37, 0
	s_waitcnt lgkmcnt(0)
	v_mfma_f32_16x16x32_bf16 v[14:17], v[2:5], v[18:21], v[14:17]
	ds_read_b128 v[2:5], v34 offset:5120
	ds_read_b128 v[34:37], v34 offset:7168
	s_mov_b32 s90, s75
	v_mfma_f32_16x16x32_bf16 v[26:29], v[26:29], v[10:13], 0
	s_mov_b32 s91, s75
	v_lshl_add_u64 v[118:119], s[34:35], 0, v[6:7]
	v_mov_b32_e32 v6, 0
	s_waitcnt lgkmcnt(0)
	v_mfma_f32_16x16x32_bf16 v[26:29], v[2:5], v[18:21], v[26:29]
	v_mov_b64_e32 v[2:3], s[88:89]
	v_mov_b64_e32 v[4:5], s[90:91]
	v_lshl_add_u64 v[116:117], s[34:35], 0, v[8:9]
	v_mfma_f32_16x16x32_bf16 v[30:33], v[34:37], v[18:21], v[30:33]
	v_max_f32_e32 v34, v25, v25
	v_max_f32_e32 v35, v24, v24
	v_max_f32_e32 v34, v35, v34
	v_max_f32_e32 v35, v17, v17
	v_max_f32_e32 v36, v16, v16
	v_max_f32_e32 v35, v36, v35
	v_max_f32_e32 v36, v27, v27
	v_max_f32_e32 v37, v26, v26
	v_max_f32_e32 v36, v37, v36
	v_max_f32_e32 v37, v29, v29
	v_max_f32_e32 v38, v28, v28
	v_max_f32_e32 v37, v38, v37
	v_max_f32_e32 v38, v33, v33
	v_max_f32_e32 v39, v32, v32
	v_max_f32_e32 v38, v39, v38
	v_max3_f32 v38, v30, v31, v38
	v_max3_f32 v34, v22, v23, v34
	v_max3_f32 v35, v14, v15, v35
	v_max3_f32 v36, v36, v37, v38
	v_max3_f32 v34, v34, v35, v36
	v_mov_b32_e32 v35, v34
	s_nop 1
	v_permlane16_swap_b32_e32 v34, v35
	v_max_f32_e32 v35, v35, v35
	v_max_f32_e32 v34, v34, v34
	v_max_f32_e32 v34, v34, v35
	v_mov_b32_e32 v35, v34
	s_nop 1
	v_permlane32_swap_b32_e32 v34, v35
	v_max_f32_e32 v35, v35, v35
	v_max_f32_e32 v34, v34, v34
	v_max_f32_e32 v113, v34, v35
	v_sub_f32_e32 v74, v22, v113
	v_sub_f32_e32 v22, v26, v113
	v_sub_f32_e32 v26, v30, v113
	v_mov_b32_e32 v30, 0
	v_sub_f32_e32 v77, v25, v113
	v_sub_f32_e32 v76, v24, v113
	v_sub_f32_e32 v75, v23, v113
	v_sub_f32_e32 v73, v17, v113
	v_sub_f32_e32 v72, v16, v113
	v_sub_f32_e32 v71, v15, v113
	v_sub_f32_e32 v70, v14, v113
	v_sub_f32_e32 v25, v29, v113
	v_sub_f32_e32 v24, v28, v113
	v_sub_f32_e32 v23, v27, v113
	v_sub_f32_e32 v29, v33, v113
	v_sub_f32_e32 v28, v32, v113
	v_sub_f32_e32 v27, v31, v113
	v_add_u32_e32 v130, s50, v127
	s_mov_b32 s36, 0
	s_mov_b32 s37, 3
	s_mov_b32 s49, 0
	s_mov_b32 s72, 0
	s_mov_b32 s50, 0
	v_mov_b32_e32 v7, v6
	v_mov_b32_e32 v8, v6
	v_mov_b32_e32 v9, v6
	v_mov_b32_e32 v14, v6
	v_mov_b32_e32 v15, v6
	v_mov_b32_e32 v16, v6
	v_mov_b32_e32 v17, v6
	v_mov_b32_e32 v31, v30
	v_mov_b32_e32 v32, v30
	v_mov_b32_e32 v33, v30
	v_mov_b32_e32 v50, v30
	v_mov_b32_e32 v51, v30
	v_mov_b32_e32 v52, v30
	v_mov_b32_e32 v53, v30
	v_mov_b32_e32 v42, v30
	v_mov_b32_e32 v43, v30
	v_mov_b32_e32 v44, v30
	v_mov_b32_e32 v45, v30
	v_mov_b32_e32 v34, v30
	v_mov_b32_e32 v35, v30
	v_mov_b32_e32 v36, v30
	v_mov_b32_e32 v37, v30
	v_mov_b32_e32 v58, v30
	v_mov_b32_e32 v59, v30
	v_mov_b32_e32 v60, v30
	v_mov_b32_e32 v61, v30
	v_mov_b32_e32 v54, v30
	v_mov_b32_e32 v55, v30
	v_mov_b32_e32 v56, v30
	v_mov_b32_e32 v57, v30
	v_mov_b32_e32 v46, v30
	v_mov_b32_e32 v47, v30
	v_mov_b32_e32 v48, v30
	v_mov_b32_e32 v49, v30
	v_mov_b32_e32 v38, v30
	v_mov_b32_e32 v39, v30
	v_mov_b32_e32 v40, v30
	v_mov_b32_e32 v41, v30
	v_mov_b32_e32 v194, 0
	v_xor_b32_e32 v150, 0x80000000, v113
	v_mov_b32_e32 v154, s48
	v_mov_b32_e32 v151, v150
	v_mov_b32_e32 v155, v154
	v_mov_b32_e32 v152, v150
	v_mov_b32_e32 v156, v154
	v_mov_b32_e32 v153, v150
	v_mov_b32_e32 v157, v154
	s_lshl_b32 s51, s49, 14
	v_add_u32_e32 v131, s51, v124
	ds_read_b128 v[204:207], v131 offset:49152
	ds_read_b128 v[208:211], v131 offset:51200
	ds_read_b128 v[212:215], v131 offset:53248
	ds_read_b128 v[216:219], v131 offset:55296
	s_mov_b64 s[88:89], s[86:87]
	s_cmp_ge_u32 s50, s0
	s_mov_b64 s[34:35], -1
	s_cbranch_scc0 .LBB0_1322

.LBB0_1326:
	s_mul_hi_u32 s34, s77, 0xaaaaaaab
	s_lshr_b32 s34, s34, 1
	s_mul_i32 s34, s34, 0xc000
	v_subrev_u32_e32 v0, s34, v130
	s_add_i32 s34, s2, s36
	v_add_u32_e32 v0, s34, v0
	ds_read_b128 v[188:191], v0
	ds_read_b128 v[82:85], v0 offset:4096
	ds_read_b128 v[94:97], v0 offset:6144
	ds_read_b128 v[98:101], v0 offset:1024
	ds_read_b128 v[86:89], v0 offset:2048
	ds_read_b128 v[132:135], v0 offset:3072
	s_waitcnt lgkmcnt(9)
	v_mfma_f32_16x16x32_bf16 v[30:33], v[204:207], v[14:17], v[30:33]
	s_waitcnt lgkmcnt(8)
	v_mfma_f32_16x16x32_bf16 v[50:53], v[208:211], v[14:17], v[50:53]
	s_waitcnt lgkmcnt(7)
	v_mfma_f32_16x16x32_bf16 v[42:45], v[212:215], v[14:17], v[42:45]
	s_waitcnt lgkmcnt(6)
	v_mfma_f32_16x16x32_bf16 v[34:37], v[216:219], v[14:17], v[34:37]
	s_waitcnt lgkmcnt(5)
	v_mfma_f32_16x16x32_bf16 v[188:191], v[188:191], v[10:13], v[150:153]
	ds_read_b128 v[78:81], v0 offset:5120
	s_waitcnt lgkmcnt(2)
	v_mfma_f32_16x16x32_bf16 v[136:139], v[86:89], v[10:13], v[150:153]
	ds_read_b128 v[86:89], v0 offset:7168
	v_mfma_f32_16x16x32_bf16 v[90:93], v[82:85], v[10:13], v[150:153]
	v_mfma_f32_16x16x32_bf16 v[94:97], v[94:97], v[10:13], v[150:153]
	v_mfma_f32_16x16x32_bf16 v[160:163], v[98:101], v[18:21], v[188:191]
	s_waitcnt lgkmcnt(2)
	v_mfma_f32_16x16x32_bf16 v[164:167], v[132:135], v[18:21], v[136:139]
	s_mov_b32 s34, 0x41000000
	v_cmp_lt_f32_e32 vcc, s34, v194
	s_cmp_lg_u64 vcc, 0
	s_cselect_b64 s[34:35], -1, 0
	s_cbranch_vccz .LBB0_1328
	v_cndmask_b32_e32 v132, 0, v194, vcc
	v_exp_f32_e64 v0, -v132
	v_sub_f32_e32 v74, v74, v132
	v_sub_f32_e32 v75, v75, v132
	v_sub_f32_e32 v76, v76, v132
	v_sub_f32_e32 v77, v77, v132
	v_sub_f32_e32 v70, v70, v132
	v_sub_f32_e32 v71, v71, v132
	v_sub_f32_e32 v72, v72, v132
	v_sub_f32_e32 v73, v73, v132
	v_sub_f32_e32 v22, v22, v132
	v_sub_f32_e32 v23, v23, v132
	v_sub_f32_e32 v24, v24, v132
	v_sub_f32_e32 v25, v25, v132
	v_sub_f32_e32 v26, v26, v132
	v_sub_f32_e32 v27, v27, v132
	v_sub_f32_e32 v28, v28, v132
	v_sub_f32_e32 v29, v29, v132
	v_add_f32_e32 v113, v113, v132
	v_xor_b32_e32 v150, 0x80000000, v113
	v_mov_b32_e32 v151, v150
	v_mov_b32_e32 v152, v150
	v_mov_b32_e32 v153, v150
	s_branch .LBB0_1329
.LBB0_1328:
.LBB0_1329:
	s_waitcnt lgkmcnt(1)
	v_mfma_f32_16x16x32_bf16 v[168:171], v[78:81], v[18:21], v[90:93]
	ds_read_b128 v[78:81], v131 offset:57344
	s_waitcnt lgkmcnt(1)
	v_mfma_f32_16x16x32_bf16 v[172:175], v[86:89], v[18:21], v[94:97]
	ds_read_b128 v[86:89], v131 offset:59392
	v_exp_f32_e32 v145, v74
	v_exp_f32_e32 v146, v75
	v_exp_f32_e32 v147, v76
	v_exp_f32_e32 v148, v77
	ds_read_b128 v[176:179], v131 offset:61440
	s_waitcnt lgkmcnt(2)
	v_mfma_f32_16x16x32_bf16 v[58:61], v[78:81], v[14:17], v[58:61]
	ds_read_b128 v[78:81], v131 offset:54272
	v_max3_f32 v195, v160, v161, v162
	v_max3_f32 v195, v195, v163, v164
	v_max3_f32 v195, v195, v165, v166
	v_max_f32_e32 v195, v195, v167
	ds_read_b128 v[82:85], v131 offset:63488
	s_waitcnt lgkmcnt(3)
	v_mfma_f32_16x16x32_bf16 v[54:57], v[86:89], v[14:17], v[54:57]
	ds_read_b128 v[86:89], v131 offset:56320
	s_cmp_ge_u32 s73, s71
	s_cbranch_scc1 .Latt_stgA_skip
	s_mul_hi_u32 s49, s50, 0xaaaaaaab
	s_lshr_b32 s49, s49, 1
	s_mul_i32 s49, s49, 0xc000
	s_sub_i32 s49, s31, s49
	s_add_i32 s49, s36, s49
	s_add_i32 s49, s2, s49
	s_lshl_b32 s51, s37, 14
	s_add_i32 s51, s76, s51
	s_mov_b32 m0, s49
	s_add_i32 s50, s51, 0xc000
	global_load_lds_dwordx4 v[114:115], off
	v_lshl_add_u64 v[192:193], v[114:115], 0, s[44:45]
	s_add_i32 m0, s49, 0x2000
	s_nop 0
	global_load_lds_dwordx4 v[192:193], off
	s_mov_b32 m0, s50
	s_nop 0
	global_load_lds_dwordx4 v[118:119], off
	s_add_i32 m0, s51, 0xe000
	s_nop 0
	global_load_lds_dwordx4 v[116:117], off
.Latt_stgA_skip:
	ds_read_b128 v[90:93], v131 offset:50176
	s_waitcnt lgkmcnt(4)
	v_mfma_f32_16x16x32_bf16 v[46:49], v[176:179], v[14:17], v[46:49]
	ds_read_b128 v[176:179], v131 offset:58368
	v_exp_f32_e32 v98, v70
	v_exp_f32_e32 v99, v71
	v_exp_f32_e32 v100, v72
	v_exp_f32_e32 v101, v73
	ds_read_b128 v[180:183], v131 offset:52224
	s_waitcnt lgkmcnt(4)
	v_mfma_f32_16x16x32_bf16 v[38:41], v[82:85], v[14:17], v[38:41]
	v_max3_f32 v194, v168, v169, v170
	v_max3_f32 v194, v194, v171, v172
	v_max3_f32 v194, v194, v173, v174
	v_max3_f32 v194, v194, v175, v195
	v_mfma_f32_16x16x32_bf16 v[2:5], v[154:157], v[14:17], v[2:5]
	v_exp_f32_e32 v102, v22
	v_exp_f32_e32 v103, v23
	v_exp_f32_e32 v104, v24
	v_exp_f32_e32 v105, v25
	ds_read_b128 v[94:97], v131 offset:60416
	s_waitcnt lgkmcnt(3)
	v_mfma_f32_16x16x32_bf16 v[30:33], v[90:93], v[6:9], v[30:33]
	ds_read_b128 v[90:93], v131 offset:62464
	v_mov_b32_e32 v158, v194
	s_nop 1
	v_permlane16_swap_b32_e32 v194, v158
	v_max_f32_e32 v194, v194, v158
	s_waitcnt lgkmcnt(2)
	v_mfma_f32_16x16x32_bf16 v[50:53], v[180:183], v[6:9], v[50:53]
	ds_read_b128 v[180:183], v131 offset:64512
	v_exp_f32_e32 v133, v26
	v_exp_f32_e32 v134, v27
	v_exp_f32_e32 v135, v28
	v_exp_f32_e32 v136, v29
	v_mfma_f32_16x16x32_bf16 v[42:45], v[78:81], v[6:9], v[42:45]
	v_mov_b32_e32 v158, v194
	s_nop 1
	v_permlane32_swap_b32_e32 v194, v158
	v_max_f32_e32 v194, v194, v158
	v_mfma_f32_16x16x32_bf16 v[34:37], v[86:89], v[6:9], v[34:37]
	v_cvt_pk_bf16_f32 v14, v145, v146
	v_cvt_pk_bf16_f32 v15, v147, v148
	v_cvt_pk_bf16_f32 v16, v98, v99
	v_cvt_pk_bf16_f32 v17, v100, v101
	v_cvt_pk_bf16_f32 v184, v102, v103
	v_cvt_pk_bf16_f32 v185, v104, v105
	v_cvt_pk_bf16_f32 v186, v133, v134
	v_cvt_pk_bf16_f32 v187, v135, v136
	v_mfma_f32_16x16x32_bf16 v[58:61], v[176:179], v[6:9], v[58:61]
	s_waitcnt lgkmcnt(2)
	v_mfma_f32_16x16x32_bf16 v[54:57], v[94:97], v[6:9], v[54:57]
	s_waitcnt lgkmcnt(1)
	v_mfma_f32_16x16x32_bf16 v[46:49], v[90:93], v[6:9], v[46:49]
	s_waitcnt lgkmcnt(0)
	v_mfma_f32_16x16x32_bf16 v[38:41], v[180:183], v[6:9], v[38:41]
	v_mfma_f32_16x16x32_bf16 v[2:5], v[154:157], v[6:9], v[2:5]
	s_andn2_b64 vcc, exec, s[34:35]
	s_cbranch_vccnz .LBB0_1331
	v_sub_f32_e32 v160, v160, v132
	v_sub_f32_e32 v161, v161, v132
	v_sub_f32_e32 v162, v162, v132
	v_sub_f32_e32 v163, v163, v132
	v_sub_f32_e32 v164, v164, v132
	v_sub_f32_e32 v165, v165, v132
	v_sub_f32_e32 v166, v166, v132
	v_sub_f32_e32 v167, v167, v132
	v_sub_f32_e32 v168, v168, v132
	v_sub_f32_e32 v169, v169, v132
	v_sub_f32_e32 v170, v170, v132
	v_sub_f32_e32 v171, v171, v132
	v_sub_f32_e32 v172, v172, v132
	v_sub_f32_e32 v173, v173, v132
	v_sub_f32_e32 v174, v174, v132
	v_sub_f32_e32 v175, v175, v132
	v_sub_f32_e32 v194, v194, v132
	v_pk_mul_f32 v[40:41], v[0:1], v[40:41] op_sel_hi:[0,1]
	v_pk_mul_f32 v[48:49], v[0:1], v[48:49] op_sel_hi:[0,1]
	v_pk_mul_f32 v[56:57], v[0:1], v[56:57] op_sel_hi:[0,1]
	v_pk_mul_f32 v[60:61], v[0:1], v[60:61] op_sel_hi:[0,1]
	v_pk_mul_f32 v[36:37], v[0:1], v[36:37] op_sel_hi:[0,1]
	v_pk_mul_f32 v[44:45], v[0:1], v[44:45] op_sel_hi:[0,1]
	v_pk_mul_f32 v[52:53], v[0:1], v[52:53] op_sel_hi:[0,1]
	v_pk_mul_f32 v[32:33], v[0:1], v[32:33] op_sel_hi:[0,1]
	v_pk_mul_f32 v[38:39], v[0:1], v[38:39] op_sel_hi:[0,1]
	v_pk_mul_f32 v[46:47], v[0:1], v[46:47] op_sel_hi:[0,1]
	v_pk_mul_f32 v[54:55], v[0:1], v[54:55] op_sel_hi:[0,1]
	v_pk_mul_f32 v[58:59], v[0:1], v[58:59] op_sel_hi:[0,1]
	v_pk_mul_f32 v[34:35], v[0:1], v[34:35] op_sel_hi:[0,1]
	v_pk_mul_f32 v[42:43], v[0:1], v[42:43] op_sel_hi:[0,1]
	v_pk_mul_f32 v[50:51], v[0:1], v[50:51] op_sel_hi:[0,1]
	v_pk_mul_f32 v[30:31], v[0:1], v[30:31] op_sel_hi:[0,1]
	v_pk_mul_f32 v[4:5], v[0:1], v[4:5] op_sel_hi:[0,1]
	v_pk_mul_f32 v[2:3], v[0:1], v[2:3] op_sel_hi:[0,1]
.LBB0_1331:
	s_add_i32 s34, s72, 1
	s_cmp_lg_u32 s72, 4
	s_cselect_b32 s34, s34, 0
	s_add_i32 s35, s37, 1
	s_cmp_lg_u32 s37, 4
	s_cselect_b32 s37, s35, 0
	s_addk_i32 s36, 0x4000
	s_add_i32 s77, s77, 1
	s_add_i32 s50, s73, -2
	v_lshl_add_u64 v[114:115], v[114:115], 0, s[74:75]
	v_lshl_add_u64 v[116:117], v[116:117], 0, s[44:45]
	s_cmp_eq_u32 s50, s71
	v_lshl_add_u64 v[118:119], v[118:119], 0, s[44:45]
	s_cbranch_scc1 .Latt_exitA
	s_mov_b32 s49, s72
	s_lshl_b32 s51, s49, 14
	v_add_u32_e32 v131, s51, v124
	ds_read_b128 v[204:207], v131 offset:49152
	ds_read_b128 v[208:211], v131 offset:51200
	ds_read_b128 v[212:215], v131 offset:53248
	ds_read_b128 v[216:219], v131 offset:55296
	s_mov_b32 s72, s34
	s_cmp_ge_u32 s50, s0
	s_mov_b64 s[34:35], -1
	s_cbranch_scc1 .Latt_B_1321
	s_branch .Latt_B_1322

.Latt_B_1326:
	s_mul_hi_u32 s34, s77, 0xaaaaaaab
	s_lshr_b32 s34, s34, 1
	s_mul_i32 s34, s34, 0xc000
	v_subrev_u32_e32 v0, s34, v130
	s_add_i32 s34, s2, s36
	v_add_u32_e32 v0, s34, v0
	ds_read_b128 v[188:191], v0
	ds_read_b128 v[82:85], v0 offset:4096
	ds_read_b128 v[94:97], v0 offset:6144
	ds_read_b128 v[98:101], v0 offset:1024
	ds_read_b128 v[86:89], v0 offset:2048
	ds_read_b128 v[132:135], v0 offset:3072
	s_waitcnt lgkmcnt(9)
	v_mfma_f32_16x16x32_bf16 v[30:33], v[204:207], v[14:17], v[30:33]
	s_waitcnt lgkmcnt(8)
	v_mfma_f32_16x16x32_bf16 v[50:53], v[208:211], v[14:17], v[50:53]
	s_waitcnt lgkmcnt(7)
	v_mfma_f32_16x16x32_bf16 v[42:45], v[212:215], v[14:17], v[42:45]
	s_waitcnt lgkmcnt(6)
	v_mfma_f32_16x16x32_bf16 v[34:37], v[216:219], v[14:17], v[34:37]
	s_waitcnt lgkmcnt(5)
	v_mfma_f32_16x16x32_bf16 v[188:191], v[188:191], v[10:13], v[150:153]
	ds_read_b128 v[78:81], v0 offset:5120
	s_waitcnt lgkmcnt(2)
	v_mfma_f32_16x16x32_bf16 v[136:139], v[86:89], v[10:13], v[150:153]
	ds_read_b128 v[86:89], v0 offset:7168
	v_mfma_f32_16x16x32_bf16 v[90:93], v[82:85], v[10:13], v[150:153]
	v_mfma_f32_16x16x32_bf16 v[94:97], v[94:97], v[10:13], v[150:153]
	v_mfma_f32_16x16x32_bf16 v[74:77], v[98:101], v[18:21], v[188:191]
	s_waitcnt lgkmcnt(2)
	v_mfma_f32_16x16x32_bf16 v[70:73], v[132:135], v[18:21], v[136:139]
	s_mov_b32 s34, 0x41000000
	v_cmp_lt_f32_e32 vcc, s34, v194
	s_cmp_lg_u64 vcc, 0
	s_cselect_b64 s[34:35], -1, 0
	s_cbranch_vccz .Latt_B_1328
	v_cndmask_b32_e32 v132, 0, v194, vcc
	v_exp_f32_e64 v0, -v132
	v_sub_f32_e32 v160, v160, v132
	v_sub_f32_e32 v161, v161, v132
	v_sub_f32_e32 v162, v162, v132
	v_sub_f32_e32 v163, v163, v132
	v_sub_f32_e32 v164, v164, v132
	v_sub_f32_e32 v165, v165, v132
	v_sub_f32_e32 v166, v166, v132
	v_sub_f32_e32 v167, v167, v132
	v_sub_f32_e32 v168, v168, v132
	v_sub_f32_e32 v169, v169, v132
	v_sub_f32_e32 v170, v170, v132
	v_sub_f32_e32 v171, v171, v132
	v_sub_f32_e32 v172, v172, v132
	v_sub_f32_e32 v173, v173, v132
	v_sub_f32_e32 v174, v174, v132
	v_sub_f32_e32 v175, v175, v132
	v_add_f32_e32 v113, v113, v132
	v_xor_b32_e32 v150, 0x80000000, v113
	v_mov_b32_e32 v151, v150
	v_mov_b32_e32 v152, v150
	v_mov_b32_e32 v153, v150
	s_branch .Latt_B_1329
.Latt_B_1328:
.Latt_B_1329:
	s_waitcnt lgkmcnt(1)
	v_mfma_f32_16x16x32_bf16 v[22:25], v[78:81], v[18:21], v[90:93]
	ds_read_b128 v[78:81], v131 offset:57344
	s_waitcnt lgkmcnt(1)
	v_mfma_f32_16x16x32_bf16 v[26:29], v[86:89], v[18:21], v[94:97]
	ds_read_b128 v[86:89], v131 offset:59392
	v_exp_f32_e32 v145, v160
	v_exp_f32_e32 v146, v161
	v_exp_f32_e32 v147, v162
	v_exp_f32_e32 v148, v163
	ds_read_b128 v[176:179], v131 offset:61440
	s_waitcnt lgkmcnt(2)
	v_mfma_f32_16x16x32_bf16 v[58:61], v[78:81], v[14:17], v[58:61]
	ds_read_b128 v[78:81], v131 offset:54272
	v_max3_f32 v195, v74, v75, v76
	v_max3_f32 v195, v195, v77, v70
	v_max3_f32 v195, v195, v71, v72
	v_max_f32_e32 v195, v195, v73
	ds_read_b128 v[82:85], v131 offset:63488
	s_waitcnt lgkmcnt(3)
	v_mfma_f32_16x16x32_bf16 v[54:57], v[86:89], v[14:17], v[54:57]
	ds_read_b128 v[86:89], v131 offset:56320
	s_cmp_ge_u32 s73, s71
	s_cbranch_scc1 .Latt_stgB_skip
	s_mul_hi_u32 s49, s50, 0xaaaaaaab
	s_lshr_b32 s49, s49, 1
	s_mul_i32 s49, s49, 0xc000
	s_sub_i32 s49, s31, s49
	s_add_i32 s49, s36, s49
	s_add_i32 s49, s2, s49
	s_lshl_b32 s51, s37, 14
	s_add_i32 s51, s76, s51
	s_mov_b32 m0, s49
	s_add_i32 s50, s51, 0xc000
	global_load_lds_dwordx4 v[114:115], off
	v_lshl_add_u64 v[192:193], v[114:115], 0, s[44:45]
	s_add_i32 m0, s49, 0x2000
	s_nop 0
	global_load_lds_dwordx4 v[192:193], off
	s_mov_b32 m0, s50
	s_nop 0
	global_load_lds_dwordx4 v[118:119], off
	s_add_i32 m0, s51, 0xe000
	s_nop 0
	global_load_lds_dwordx4 v[116:117], off
.Latt_stgB_skip:
	ds_read_b128 v[90:93], v131 offset:50176
	s_waitcnt lgkmcnt(4)
	v_mfma_f32_16x16x32_bf16 v[46:49], v[176:179], v[14:17], v[46:49]
	ds_read_b128 v[176:179], v131 offset:58368
	v_exp_f32_e32 v98, v164
	v_exp_f32_e32 v99, v165
	v_exp_f32_e32 v100, v166
	v_exp_f32_e32 v101, v167
	ds_read_b128 v[180:183], v131 offset:52224
	s_waitcnt lgkmcnt(4)
	v_mfma_f32_16x16x32_bf16 v[38:41], v[82:85], v[14:17], v[38:41]
	v_max3_f32 v194, v22, v23, v24
	v_max3_f32 v194, v194, v25, v26
	v_max3_f32 v194, v194, v27, v28
	v_max3_f32 v194, v194, v29, v195
	v_mfma_f32_16x16x32_bf16 v[2:5], v[154:157], v[14:17], v[2:5]
	v_exp_f32_e32 v102, v168
	v_exp_f32_e32 v103, v169
	v_exp_f32_e32 v104, v170
	v_exp_f32_e32 v105, v171
	ds_read_b128 v[94:97], v131 offset:60416
	s_waitcnt lgkmcnt(3)
	v_mfma_f32_16x16x32_bf16 v[30:33], v[90:93], v[184:187], v[30:33]
	ds_read_b128 v[90:93], v131 offset:62464
	v_mov_b32_e32 v158, v194
	s_nop 1
	v_permlane16_swap_b32_e32 v194, v158
	v_max_f32_e32 v194, v194, v158
	s_waitcnt lgkmcnt(2)
	v_mfma_f32_16x16x32_bf16 v[50:53], v[180:183], v[184:187], v[50:53]
	ds_read_b128 v[180:183], v131 offset:64512
	v_exp_f32_e32 v133, v172
	v_exp_f32_e32 v134, v173
	v_exp_f32_e32 v135, v174
	v_exp_f32_e32 v136, v175
	v_mfma_f32_16x16x32_bf16 v[42:45], v[78:81], v[184:187], v[42:45]
	v_mov_b32_e32 v158, v194
	s_nop 1
	v_permlane32_swap_b32_e32 v194, v158
	v_max_f32_e32 v194, v194, v158
	v_mfma_f32_16x16x32_bf16 v[34:37], v[86:89], v[184:187], v[34:37]
	v_cvt_pk_bf16_f32 v14, v145, v146
	v_cvt_pk_bf16_f32 v15, v147, v148
	v_cvt_pk_bf16_f32 v16, v98, v99
	v_cvt_pk_bf16_f32 v17, v100, v101
	v_cvt_pk_bf16_f32 v6, v102, v103
	v_cvt_pk_bf16_f32 v7, v104, v105
	v_cvt_pk_bf16_f32 v8, v133, v134
	v_cvt_pk_bf16_f32 v9, v135, v136
	v_mfma_f32_16x16x32_bf16 v[58:61], v[176:179], v[184:187], v[58:61]
	s_waitcnt lgkmcnt(2)
	v_mfma_f32_16x16x32_bf16 v[54:57], v[94:97], v[184:187], v[54:57]
	s_waitcnt lgkmcnt(1)
	v_mfma_f32_16x16x32_bf16 v[46:49], v[90:93], v[184:187], v[46:49]
	s_waitcnt lgkmcnt(0)
	v_mfma_f32_16x16x32_bf16 v[38:41], v[180:183], v[184:187], v[38:41]
	v_mfma_f32_16x16x32_bf16 v[2:5], v[154:157], v[184:187], v[2:5]
	s_andn2_b64 vcc, exec, s[34:35]
	s_cbranch_vccnz .Latt_B_1331
	v_sub_f32_e32 v74, v74, v132
	v_sub_f32_e32 v75, v75, v132
	v_sub_f32_e32 v76, v76, v132
	v_sub_f32_e32 v77, v77, v132
	v_sub_f32_e32 v70, v70, v132
	v_sub_f32_e32 v71, v71, v132
	v_sub_f32_e32 v72, v72, v132
	v_sub_f32_e32 v73, v73, v132
	v_sub_f32_e32 v22, v22, v132
	v_sub_f32_e32 v23, v23, v132
	v_sub_f32_e32 v24, v24, v132
	v_sub_f32_e32 v25, v25, v132
	v_sub_f32_e32 v26, v26, v132
	v_sub_f32_e32 v27, v27, v132
	v_sub_f32_e32 v28, v28, v132
	v_sub_f32_e32 v29, v29, v132
	v_sub_f32_e32 v194, v194, v132
	v_pk_mul_f32 v[40:41], v[0:1], v[40:41] op_sel_hi:[0,1]
	v_pk_mul_f32 v[48:49], v[0:1], v[48:49] op_sel_hi:[0,1]
	v_pk_mul_f32 v[56:57], v[0:1], v[56:57] op_sel_hi:[0,1]
	v_pk_mul_f32 v[60:61], v[0:1], v[60:61] op_sel_hi:[0,1]
	v_pk_mul_f32 v[36:37], v[0:1], v[36:37] op_sel_hi:[0,1]
	v_pk_mul_f32 v[44:45], v[0:1], v[44:45] op_sel_hi:[0,1]
	v_pk_mul_f32 v[52:53], v[0:1], v[52:53] op_sel_hi:[0,1]
	v_pk_mul_f32 v[32:33], v[0:1], v[32:33] op_sel_hi:[0,1]
	v_pk_mul_f32 v[38:39], v[0:1], v[38:39] op_sel_hi:[0,1]
	v_pk_mul_f32 v[46:47], v[0:1], v[46:47] op_sel_hi:[0,1]
	v_pk_mul_f32 v[54:55], v[0:1], v[54:55] op_sel_hi:[0,1]
	v_pk_mul_f32 v[58:59], v[0:1], v[58:59] op_sel_hi:[0,1]
	v_pk_mul_f32 v[34:35], v[0:1], v[34:35] op_sel_hi:[0,1]
	v_pk_mul_f32 v[42:43], v[0:1], v[42:43] op_sel_hi:[0,1]
	v_pk_mul_f32 v[50:51], v[0:1], v[50:51] op_sel_hi:[0,1]
	v_pk_mul_f32 v[30:31], v[0:1], v[30:31] op_sel_hi:[0,1]
	v_pk_mul_f32 v[4:5], v[0:1], v[4:5] op_sel_hi:[0,1]
	v_pk_mul_f32 v[2:3], v[0:1], v[2:3] op_sel_hi:[0,1]
